# nt cache-policy hint on the rowwise phases once-touched streams (x and src loads, x stores)
# speedup vs baseline: 1.0051x; 1.0051x over previous
; DI float lo2f(unsigned v) { return __uint_as_float(v << 16); }
; DI float hi2f(unsigned v) { return __uint_as_float(v & 0xffff0000u); }
; DI void phase_rowwise(PP p, bool first, const u16* src, const float* g_post, int l_res, int gate_idx,
;                       bool write_h, const float* g_pre, int l_mod, int shift_idx, int scale_idx, bool skip_ctx) {
;     ...
;     const float* xin = xrow_in(p, r, first);
;     float x[16];
; #pragma unroll
;     for (int i = 0; i < 4; ++i) { F4 v = *(const F4*)(xin + i * 256 + lane * 4); x[4 * i] = v.x; x[4 * i + 1] = v.y; x[4 * i + 2] = v.z; x[4 * i + 3] = v.w; }
;     if (src) {
;       float y[16]; float ss = 0.f;
; #pragma unroll
;       for (int i = 0; i < 4; ++i) { U2 v = *(const U2*)(src + (size_t)r * DM + i * 256 + lane * 4);
;         y[4 * i] = lo2f(v.x); y[4 * i + 1] = hi2f(v.x); y[4 * i + 2] = lo2f(v.y); y[4 * i + 3] = hi2f(v.y); }
.Lrw20_first_ok:
	s_lshl_b32 s7, s2, 8
	s_add_i32 s7, s7, s3
	s_lshl_b32 s12, s2, 13
	s_add_i32 s12, s12, s3
	s_add_i32 s12, s12, 0xffffff00
	s_cmp_eq_u32 s6, 1
	s_cselect_b32 s7, s7, s12
	s_cselect_b32 s9, 4, s2
	s_cselect_b64 s[12:13], -1, 0
	s_lshl_b32 s7, s7, 12
	v_add_u32_e32 v74, s7, v2
	v_cndmask_b32_e64 v0, v234, v236, s[12:13]
	v_cndmask_b32_e64 v227, v235, v237, s[12:13]
	v_mov_b32_e32 v190, v0
	v_mov_b32_e32 v191, v227
	v_lshl_add_u64 v[190:191], v[190:191], 0, v[74:75]
	v_cndmask_b32_e64 v192, v230, v232, s[12:13]
	v_cndmask_b32_e64 v193, v231, v233, s[12:13]
	v_lshl_add_u64 v[192:193], v[192:193], 0, v[74:75]
	s_lshl_b32 s7, s0, 11
	v_mov_b32_e32 v74, s7
	v_lshl_add_u64 v[196:197], v[180:181], 0, v[74:75]
	global_load_dwordx4 v[26:29], v[190:191], off nt
	global_load_dwordx4 v[30:33], v[190:191], off offset:1024 nt
	global_load_dwordx4 v[34:37], v[190:191], off offset:2048 nt
	global_load_dwordx4 v[38:41], v[190:191], off offset:3072 nt
	global_load_dwordx2 v[42:43], v[196:197], off nt
	global_load_dwordx2 v[44:45], v[196:197], off offset:512 nt
	global_load_dwordx2 v[46:47], v[196:197], off offset:1024 nt
	global_load_dwordx2 v[48:49], v[196:197], off offset:1536 nt
	s_waitcnt vmcnt(0)
	s_branch .Lrw20_loop

; DI float lo2f(unsigned v) { return __uint_as_float(v << 16); }
; DI float hi2f(unsigned v) { return __uint_as_float(v & 0xffff0000u); }
; DI float wave_sum(float v) { for (int o = 32; o > 0; o >>= 1) v += __shfl_xor(v, o); return v; }
; DI void phase_rowwise(PP p, bool first, const u16* src, const float* g_post, int l_res, int gate_idx,
;                       bool write_h, const float* g_pre, int l_mod, int shift_idx, int scale_idx, bool skip_ctx) {
;     ...
;     const float* xin = xrow_in(p, r, first);
;     float x[16];
; #pragma unroll
;     for (int i = 0; i < 4; ++i) { F4 v = *(const F4*)(xin + i * 256 + lane * 4); x[4 * i] = v.x; x[4 * i + 1] = v.y; x[4 * i + 2] = v.z; x[4 * i + 3] = v.w; }
;     if (src) {
;       float y[16]; float ss = 0.f;
; #pragma unroll
;       for (int i = 0; i < 4; ++i) { U2 v = *(const U2*)(src + (size_t)r * DM + i * 256 + lane * 4);
;         y[4 * i] = lo2f(v.x); y[4 * i + 1] = hi2f(v.x); y[4 * i + 2] = lo2f(v.y); y[4 * i + 3] = hi2f(v.y); }
; #pragma unroll
;       for (int i = 0; i < 16; ++i) ss += y[i] * y[i];
;       ss = wave_sum(ss);
;       float rstd = rsqrtf(ss * (1.f / DM) + EPS);
.Lrw20_nxt_go:
	s_lshl_b32 s7, s2, 8
	s_add_i32 s7, s7, s3
	s_lshl_b32 s12, s2, 13
	s_add_i32 s12, s12, s3
	s_add_i32 s12, s12, 0xffffff00
	s_cmp_eq_u32 s6, 1
	s_cselect_b32 s7, s7, s12
	s_cselect_b32 s9, 4, s2
	s_cselect_b64 s[12:13], -1, 0
	s_lshl_b32 s7, s7, 12
	v_add_u32_e32 v74, s7, v2
	v_cndmask_b32_e64 v0, v234, v236, s[12:13]
	v_cndmask_b32_e64 v227, v235, v237, s[12:13]
	v_mov_b32_e32 v190, v0
	v_mov_b32_e32 v191, v227
	v_lshl_add_u64 v[190:191], v[190:191], 0, v[74:75]
	v_cndmask_b32_e64 v192, v230, v232, s[12:13]
	v_cndmask_b32_e64 v193, v231, v233, s[12:13]
	v_lshl_add_u64 v[192:193], v[192:193], 0, v[74:75]
	s_lshl_b32 s7, s1, 11
	v_mov_b32_e32 v74, s7
	v_lshl_add_u64 v[196:197], v[180:181], 0, v[74:75]
	global_load_dwordx4 v[26:29], v[190:191], off nt
	global_load_dwordx4 v[30:33], v[190:191], off offset:1024 nt
	global_load_dwordx4 v[34:37], v[190:191], off offset:2048 nt
	global_load_dwordx4 v[38:41], v[190:191], off offset:3072 nt
	global_load_dwordx2 v[42:43], v[196:197], off nt
	global_load_dwordx2 v[44:45], v[196:197], off offset:512 nt
	global_load_dwordx2 v[46:47], v[196:197], off offset:1024 nt
	global_load_dwordx2 v[48:49], v[196:197], off offset:1536 nt
	v_lshlrev_b32_e32 v58, 16, v50
	v_and_b32_e32 v59, 0xffff0000, v50
	v_lshlrev_b32_e32 v60, 16, v51
	v_and_b32_e32 v61, 0xffff0000, v51
	v_lshlrev_b32_e32 v62, 16, v52
	v_and_b32_e32 v63, 0xffff0000, v52
	v_lshlrev_b32_e32 v64, 16, v53
	v_and_b32_e32 v65, 0xffff0000, v53
	v_lshlrev_b32_e32 v66, 16, v54
	v_and_b32_e32 v67, 0xffff0000, v54
	v_lshlrev_b32_e32 v68, 16, v55
	v_and_b32_e32 v69, 0xffff0000, v55
	v_lshlrev_b32_e32 v70, 16, v56
	v_and_b32_e32 v71, 0xffff0000, v56
	v_lshlrev_b32_e32 v72, 16, v57
	v_and_b32_e32 v73, 0xffff0000, v57
	v_mul_f32_e32 v226, v58, v58
	v_mul_f32_e32 v227, v59, v59
	v_add_f32_e32 v226, v226, v227
	v_mul_f32_e32 v227, v60, v60
	v_add_f32_e32 v226, v227, v226
	v_mul_f32_e32 v227, v61, v61
	v_add_f32_e32 v226, v227, v226
	v_mul_f32_e32 v227, v62, v62
	v_add_f32_e32 v226, v227, v226
	v_mul_f32_e32 v227, v63, v63
	v_add_f32_e32 v226, v227, v226
	v_mul_f32_e32 v227, v64, v64
	v_add_f32_e32 v226, v227, v226
	v_mul_f32_e32 v227, v65, v65
	v_add_f32_e32 v226, v227, v226
	v_mul_f32_e32 v227, v66, v66
	v_add_f32_e32 v226, v227, v226
	v_mul_f32_e32 v227, v67, v67
	v_add_f32_e32 v226, v227, v226
	v_mul_f32_e32 v227, v68, v68
	v_add_f32_e32 v226, v227, v226
	v_mul_f32_e32 v227, v69, v69
	v_add_f32_e32 v226, v227, v226
	v_mul_f32_e32 v227, v70, v70
	v_add_f32_e32 v226, v227, v226
	v_mul_f32_e32 v227, v71, v71
	v_add_f32_e32 v226, v227, v226
	v_mul_f32_e32 v227, v72, v72
	v_add_f32_e32 v226, v227, v226
	v_mul_f32_e32 v227, v73, v73
	v_add_f32_e32 v226, v227, v226
	ds_bpermute_b32 v227, v4, v226
	s_waitcnt lgkmcnt(0)
	v_add_f32_e32 v226, v226, v227
	ds_bpermute_b32 v227, v5, v226
	s_waitcnt lgkmcnt(0)
	v_add_f32_e32 v226, v226, v227
	ds_bpermute_b32 v227, v6, v226
	s_waitcnt lgkmcnt(0)
	v_add_f32_e32 v226, v226, v227
	ds_bpermute_b32 v227, v7, v226
	s_waitcnt lgkmcnt(0)
	v_add_f32_e32 v226, v226, v227
	ds_bpermute_b32 v227, v8, v226
	s_waitcnt lgkmcnt(0)
	v_add_f32_e32 v226, v226, v227
	ds_bpermute_b32 v227, v9, v226
	s_waitcnt lgkmcnt(0)
	v_add_f32_e32 v226, v226, v227
	v_fmamk_f32 v226, v226, 0x3a800000, v162
	s_mov_b32 s7, 0x800000
	v_cmp_gt_f32_e32 vcc, s7, v226
	v_mul_f32_e32 v227, 0x4b800000, v226
	s_nop 0
	v_cndmask_b32_e32 v226, v226, v227, vcc
	v_rsq_f32_e32 v226, v226
	s_nop 0
	v_mul_f32_e32 v227, 0x45800000, v226
	v_cndmask_b32_e32 v228, v226, v227, vcc
	s_waitcnt vmcnt(8)
	v_pk_mul_f32 v[58:59], v[228:229], v[58:59] op_sel_hi:[0,1]
	v_pk_mul_f32 v[58:59], v[58:59], v[118:119]
	v_pk_fma_f32 v[10:11], v[134:135], v[58:59], v[10:11]
	v_pk_mul_f32 v[60:61], v[228:229], v[60:61] op_sel_hi:[0,1]
	v_pk_mul_f32 v[60:61], v[60:61], v[120:121]
	v_pk_fma_f32 v[12:13], v[136:137], v[60:61], v[12:13]
	v_pk_mul_f32 v[62:63], v[228:229], v[62:63] op_sel_hi:[0,1]
	v_pk_mul_f32 v[62:63], v[62:63], v[122:123]
	v_pk_fma_f32 v[14:15], v[138:139], v[62:63], v[14:15]
	v_pk_mul_f32 v[64:65], v[228:229], v[64:65] op_sel_hi:[0,1]
	v_pk_mul_f32 v[64:65], v[64:65], v[124:125]
	v_pk_fma_f32 v[16:17], v[140:141], v[64:65], v[16:17]
	v_pk_mul_f32 v[66:67], v[228:229], v[66:67] op_sel_hi:[0,1]
	v_pk_mul_f32 v[66:67], v[66:67], v[126:127]
	v_pk_fma_f32 v[18:19], v[142:143], v[66:67], v[18:19]
	v_pk_mul_f32 v[68:69], v[228:229], v[68:69] op_sel_hi:[0,1]
	v_pk_mul_f32 v[68:69], v[68:69], v[128:129]
	v_pk_fma_f32 v[20:21], v[144:145], v[68:69], v[20:21]
	v_pk_mul_f32 v[70:71], v[228:229], v[70:71] op_sel_hi:[0,1]
	v_pk_mul_f32 v[70:71], v[70:71], v[130:131]
	v_pk_fma_f32 v[22:23], v[146:147], v[70:71], v[22:23]
	v_pk_mul_f32 v[72:73], v[228:229], v[72:73] op_sel_hi:[0,1]
	v_pk_mul_f32 v[72:73], v[72:73], v[132:133]
	v_pk_fma_f32 v[24:25], v[148:149], v[72:73], v[24:25]
	s_cmp_eq_u32 s10, 1
	s_cbranch_scc1 .Lrw20_noh_st
; DI unsigned pack2(float a, float b) { F2 v = {a, b}; B2 r = __builtin_convertvector(v, B2); return __builtin_bit_cast(unsigned, r); }
; DI float wave_sum(float v) { for (int o = 32; o > 0; o >>= 1) v += __shfl_xor(v, o); return v; }
; DI const float* modvec(PP p, int l, int s, int idx) { return (const float*)(p->ws + S_MOD) + ((size_t)(l * 5 + s) * 6 + idx) * DM; }
; DI void phase_rowwise(PP p, bool first, const u16* src, const float* g_post, int l_res, int gate_idx,
;                       bool write_h, const float* g_pre, int l_mod, int shift_idx, int scale_idx, bool skip_ctx) {
;     ...
;         *(F4*)(xo + k) = mkf4(x[4 * i], x[4 * i + 1], x[4 * i + 2], x[4 * i + 3]);
;       }
;     }
;     if (write_h) {
;       float ss = 0.f;
; #pragma unroll
;       for (int i = 0; i < 16; ++i) ss += x[i] * x[i];
;       ss = wave_sum(ss);
;       float rstd = rsqrtf(ss * (1.f / DM) + EPS);
;       const float* sh = modvec(p, l_mod, s, shift_idx); const float* sc = modvec(p, l_mod, s, scale_idx);
; #pragma unroll
;       for (int i = 0; i < 4; ++i) {
;         int k = i * 256 + lane * 4;
;         F4 g = *(const F4*)(g_pre + k); F4 a = *(const F4*)(sh + k); F4 c = *(const F4*)(sc + k);
;         float h0 = x[4 * i] * rstd * g.x * (1.f + c.x) + a.x, h1 = x[4 * i + 1] * rstd * g.y * (1.f + c.y) + a.y;
;         float h2 = x[4 * i + 2] * rstd * g.z * (1.f + c.z) + a.z, h3 = x[4 * i + 3] * rstd * g.w * (1.f + c.w) + a.w;
;         *(U2*)(H + (size_t)r * DM + k) = mku2(pack2(h0, h1), pack2(h2, h3));
;       }
	global_load_dwordx4 v[118:121], v[172:173], off
	global_load_dwordx4 v[122:125], v[172:173], off offset:1024
	global_load_dwordx4 v[126:129], v[172:173], off offset:2048
	global_load_dwordx4 v[130:133], v[172:173], off offset:3072
	global_load_dwordx4 v[134:137], v[222:223], off
	global_load_dwordx4 v[138:141], v[222:223], off offset:1024
	global_load_dwordx4 v[142:145], v[222:223], off offset:2048
	global_load_dwordx4 v[146:149], v[222:223], off offset:3072
	global_load_dwordx4 v[150:153], v[224:225], off
	global_load_dwordx4 v[154:157], v[224:225], off offset:1024
	global_load_dwordx4 v[158:161], v[224:225], off offset:2048
	global_load_dwordx4 v[166:169], v[224:225], off offset:3072
	global_store_dwordx4 v[188:189], v[10:13], off nt
	global_store_dwordx4 v[188:189], v[14:17], off offset:1024 nt
	global_store_dwordx4 v[188:189], v[18:21], off offset:2048 nt
	global_store_dwordx4 v[188:189], v[22:25], off offset:3072 nt
	v_mul_f32_e32 v226, v10, v10
	v_mul_f32_e32 v227, v11, v11
	v_add_f32_e32 v226, v226, v227
	v_mul_f32_e32 v227, v12, v12
	v_add_f32_e32 v226, v227, v226
	v_mul_f32_e32 v227, v13, v13
	v_add_f32_e32 v226, v227, v226
	v_mul_f32_e32 v227, v14, v14
	v_add_f32_e32 v226, v227, v226
	v_mul_f32_e32 v227, v15, v15
	v_add_f32_e32 v226, v227, v226
	v_mul_f32_e32 v227, v16, v16
	v_add_f32_e32 v226, v227, v226
	v_mul_f32_e32 v227, v17, v17
	v_add_f32_e32 v226, v227, v226
	v_mul_f32_e32 v227, v18, v18
	v_add_f32_e32 v226, v227, v226
	v_mul_f32_e32 v227, v19, v19
	v_add_f32_e32 v226, v227, v226
	v_mul_f32_e32 v227, v20, v20
	v_add_f32_e32 v226, v227, v226
	v_mul_f32_e32 v227, v21, v21
	v_add_f32_e32 v226, v227, v226
	v_mul_f32_e32 v227, v22, v22
	v_add_f32_e32 v226, v227, v226
	v_mul_f32_e32 v227, v23, v23
	v_add_f32_e32 v226, v227, v226
	v_mul_f32_e32 v227, v24, v24
	v_add_f32_e32 v226, v227, v226
	v_mul_f32_e32 v227, v25, v25
	v_add_f32_e32 v226, v227, v226
	ds_bpermute_b32 v227, v4, v226
	s_waitcnt lgkmcnt(0)
	v_add_f32_e32 v226, v226, v227
	ds_bpermute_b32 v227, v5, v226
	s_waitcnt lgkmcnt(0)
	v_add_f32_e32 v226, v226, v227
	ds_bpermute_b32 v227, v6, v226
	s_waitcnt lgkmcnt(0)
	v_add_f32_e32 v226, v226, v227
	ds_bpermute_b32 v227, v7, v226
	s_waitcnt lgkmcnt(0)
	v_add_f32_e32 v226, v226, v227
	ds_bpermute_b32 v227, v8, v226
	s_waitcnt lgkmcnt(0)
	v_add_f32_e32 v226, v226, v227
	ds_bpermute_b32 v227, v9, v226
	s_waitcnt lgkmcnt(0)
	v_add_f32_e32 v226, v226, v227
	v_fmamk_f32 v226, v226, 0x3a800000, v162
	s_mov_b32 s7, 0x800000
	v_cmp_gt_f32_e32 vcc, s7, v226
	v_mul_f32_e32 v227, 0x4b800000, v226
	s_nop 0
	v_cndmask_b32_e32 v226, v226, v227, vcc
	v_rsq_f32_e32 v226, v226
	s_nop 0
	v_mul_f32_e32 v227, 0x45800000, v226
	v_cndmask_b32_e32 v228, v226, v227, vcc
	s_waitcnt vmcnt(4)
	v_pk_mul_f32 v[10:11], v[10:11], v[228:229] op_sel_hi:[1,0]
	v_pk_mul_f32 v[10:11], v[118:119], v[10:11]
	v_pk_add_f32 v[58:59], v[150:151], 1.0 op_sel_hi:[1,0]
	s_nop 0
	v_pk_fma_f32 v[10:11], v[58:59], v[10:11], v[134:135]
	v_pk_mul_f32 v[12:13], v[12:13], v[228:229] op_sel_hi:[1,0]
	v_pk_mul_f32 v[12:13], v[120:121], v[12:13]
	v_pk_add_f32 v[60:61], v[152:153], 1.0 op_sel_hi:[1,0]
	s_nop 0
	v_pk_fma_f32 v[12:13], v[60:61], v[12:13], v[136:137]
	v_cvt_pk_bf16_f32 v66, v10, v11
	v_cvt_pk_bf16_f32 v67, v12, v13
	global_store_dwordx2 v[218:219], v[66:67], off
	s_nop 1
	v_pk_mul_f32 v[14:15], v[14:15], v[228:229] op_sel_hi:[1,0]
	v_pk_mul_f32 v[14:15], v[122:123], v[14:15]
	v_pk_add_f32 v[58:59], v[154:155], 1.0 op_sel_hi:[1,0]
	s_nop 0
	v_pk_fma_f32 v[14:15], v[58:59], v[14:15], v[138:139]
	v_pk_mul_f32 v[16:17], v[16:17], v[228:229] op_sel_hi:[1,0]
	v_pk_mul_f32 v[16:17], v[124:125], v[16:17]
	v_pk_add_f32 v[60:61], v[156:157], 1.0 op_sel_hi:[1,0]
	s_nop 0
	v_pk_fma_f32 v[16:17], v[60:61], v[16:17], v[140:141]
	v_cvt_pk_bf16_f32 v66, v14, v15
	v_cvt_pk_bf16_f32 v67, v16, v17
	global_store_dwordx2 v[218:219], v[66:67], off offset:512
	s_nop 1
	v_pk_mul_f32 v[18:19], v[18:19], v[228:229] op_sel_hi:[1,0]
	v_pk_mul_f32 v[18:19], v[126:127], v[18:19]
	v_pk_add_f32 v[58:59], v[158:159], 1.0 op_sel_hi:[1,0]
	s_nop 0
	v_pk_fma_f32 v[18:19], v[58:59], v[18:19], v[142:143]
	v_pk_mul_f32 v[20:21], v[20:21], v[228:229] op_sel_hi:[1,0]
	v_pk_mul_f32 v[20:21], v[128:129], v[20:21]
	v_pk_add_f32 v[60:61], v[160:161], 1.0 op_sel_hi:[1,0]
	s_nop 0
	v_pk_fma_f32 v[20:21], v[60:61], v[20:21], v[144:145]
	v_cvt_pk_bf16_f32 v66, v18, v19
	v_cvt_pk_bf16_f32 v67, v20, v21
	global_store_dwordx2 v[218:219], v[66:67], off offset:1024
	s_nop 1
	v_pk_mul_f32 v[22:23], v[22:23], v[228:229] op_sel_hi:[1,0]
	v_pk_mul_f32 v[22:23], v[130:131], v[22:23]
	v_pk_add_f32 v[58:59], v[166:167], 1.0 op_sel_hi:[1,0]
	s_nop 0
	v_pk_fma_f32 v[22:23], v[58:59], v[22:23], v[146:147]
	v_pk_mul_f32 v[24:25], v[24:25], v[228:229] op_sel_hi:[1,0]
	v_pk_mul_f32 v[24:25], v[132:133], v[24:25]
	v_pk_add_f32 v[60:61], v[168:169], 1.0 op_sel_hi:[1,0]
	s_nop 0
	v_pk_fma_f32 v[24:25], v[60:61], v[24:25], v[148:149]
	v_cvt_pk_bf16_f32 v66, v22, v23
	v_cvt_pk_bf16_f32 v67, v24, v25
	global_store_dwordx2 v[218:219], v[66:67], off offset:1536
	s_nop 1
	s_branch .Lrw20_noh
.Lrw20_noh_st:
	global_store_dwordx4 v[188:189], v[10:13], off nt
	global_store_dwordx4 v[188:189], v[14:17], off offset:1024 nt
	global_store_dwordx4 v[188:189], v[18:21], off offset:2048 nt
	global_store_dwordx4 v[188:189], v[22:25], off offset:3072 nt
	s_waitcnt vmcnt(4)

; DI float lo2f(unsigned v) { return __uint_as_float(v << 16); }
; DI float hi2f(unsigned v) { return __uint_as_float(v & 0xffff0000u); }
; DI float wave_sum(float v) { for (int o = 32; o > 0; o >>= 1) v += __shfl_xor(v, o); return v; }
; DI void phase_rowwise(PP p, bool first, const u16* src, const float* g_post, int l_res, int gate_idx,
;                       bool write_h, const float* g_pre, int l_mod, int shift_idx, int scale_idx, bool skip_ctx) {
;     ...
;     int b = r / TT, t = r - b * TT;
;     if (skip_ctx && t < CTX) continue;
;     int s = t < CTX ? 4 : b;
;     const float* xin = xrow_in(p, r, first);
;     float x[16];
; #pragma unroll
;     for (int i = 0; i < 4; ++i) { F4 v = *(const F4*)(xin + i * 256 + lane * 4); x[4 * i] = v.x; x[4 * i + 1] = v.y; x[4 * i + 2] = v.z; x[4 * i + 3] = v.w; }
;     if (src) {
;       float y[16]; float ss = 0.f;
; #pragma unroll
;       for (int i = 0; i < 4; ++i) { U2 v = *(const U2*)(src + (size_t)r * DM + i * 256 + lane * 4);
;         y[4 * i] = lo2f(v.x); y[4 * i + 1] = hi2f(v.x); y[4 * i + 2] = lo2f(v.y); y[4 * i + 3] = hi2f(v.y); }
; #pragma unroll
;       for (int i = 0; i < 16; ++i) ss += y[i] * y[i];
;       ss = wave_sum(ss);
;       float rstd = rsqrtf(ss * (1.f / DM) + EPS);
.Lrw17_nxt_go:
	s_lshl_b32 s7, s2, 8
	s_add_i32 s7, s7, s3
	s_lshl_b32 s12, s2, 13
	s_add_i32 s12, s12, s3
	s_add_i32 s12, s12, 0xffffff00
	s_cmp_eq_u32 s6, 1
	s_cselect_b32 s7, s7, s12
	s_cselect_b32 s9, 4, s2
	s_cselect_b64 s[12:13], -1, 0
	s_lshl_b32 s7, s7, 12
	v_add_u32_e32 v74, s7, v2
	v_cndmask_b32_e64 v0, v234, v236, s[12:13]
	v_cndmask_b32_e64 v227, v235, v237, s[12:13]
	v_mov_b32_e32 v190, v0
	v_mov_b32_e32 v191, v227
	v_lshl_add_u64 v[190:191], v[190:191], 0, v[74:75]
	v_cndmask_b32_e64 v192, v230, v232, s[12:13]
	v_cndmask_b32_e64 v193, v231, v233, s[12:13]
	v_lshl_add_u64 v[192:193], v[192:193], 0, v[74:75]
	s_lshl_b32 s7, s1, 11
	v_mov_b32_e32 v74, s7
	v_lshl_add_u64 v[196:197], v[180:181], 0, v[74:75]
	global_load_dwordx4 v[26:29], v[190:191], off nt
	global_load_dwordx4 v[30:33], v[190:191], off offset:1024 nt
	global_load_dwordx4 v[34:37], v[190:191], off offset:2048 nt
	global_load_dwordx4 v[38:41], v[190:191], off offset:3072 nt
	global_load_dwordx2 v[42:43], v[196:197], off nt
	global_load_dwordx2 v[44:45], v[196:197], off offset:512 nt
	global_load_dwordx2 v[46:47], v[196:197], off offset:1024 nt
	global_load_dwordx2 v[48:49], v[196:197], off offset:1536 nt
	v_lshlrev_b32_e32 v58, 16, v50
	v_and_b32_e32 v59, 0xffff0000, v50
	v_lshlrev_b32_e32 v60, 16, v51
	v_and_b32_e32 v61, 0xffff0000, v51
	v_lshlrev_b32_e32 v62, 16, v52
	v_and_b32_e32 v63, 0xffff0000, v52
	v_lshlrev_b32_e32 v64, 16, v53
	v_and_b32_e32 v65, 0xffff0000, v53
	v_lshlrev_b32_e32 v66, 16, v54
	v_and_b32_e32 v67, 0xffff0000, v54
	v_lshlrev_b32_e32 v68, 16, v55
	v_and_b32_e32 v69, 0xffff0000, v55
	v_lshlrev_b32_e32 v70, 16, v56
	v_and_b32_e32 v71, 0xffff0000, v56
	v_lshlrev_b32_e32 v72, 16, v57
	v_and_b32_e32 v73, 0xffff0000, v57
	v_mul_f32_e32 v226, v58, v58
	v_mul_f32_e32 v227, v59, v59
	v_add_f32_e32 v226, v226, v227
	v_mul_f32_e32 v227, v60, v60
	v_add_f32_e32 v226, v227, v226
	v_mul_f32_e32 v227, v61, v61
	v_add_f32_e32 v226, v227, v226
	v_mul_f32_e32 v227, v62, v62
	v_add_f32_e32 v226, v227, v226
	v_mul_f32_e32 v227, v63, v63
	v_add_f32_e32 v226, v227, v226
	v_mul_f32_e32 v227, v64, v64
	v_add_f32_e32 v226, v227, v226
	v_mul_f32_e32 v227, v65, v65
	v_add_f32_e32 v226, v227, v226
	v_mul_f32_e32 v227, v66, v66
	v_add_f32_e32 v226, v227, v226
	v_mul_f32_e32 v227, v67, v67
	v_add_f32_e32 v226, v227, v226
	v_mul_f32_e32 v227, v68, v68
	v_add_f32_e32 v226, v227, v226
	v_mul_f32_e32 v227, v69, v69
	v_add_f32_e32 v226, v227, v226
	v_mul_f32_e32 v227, v70, v70
	v_add_f32_e32 v226, v227, v226
	v_mul_f32_e32 v227, v71, v71
	v_add_f32_e32 v226, v227, v226
	v_mul_f32_e32 v227, v72, v72
	v_add_f32_e32 v226, v227, v226
	v_mul_f32_e32 v227, v73, v73
	v_add_f32_e32 v226, v227, v226
	ds_bpermute_b32 v227, v4, v226
	s_waitcnt lgkmcnt(0)
	v_add_f32_e32 v226, v226, v227
	ds_bpermute_b32 v227, v5, v226
	s_waitcnt lgkmcnt(0)
	v_add_f32_e32 v226, v226, v227
	ds_bpermute_b32 v227, v6, v226
	s_waitcnt lgkmcnt(0)
	v_add_f32_e32 v226, v226, v227
	ds_bpermute_b32 v227, v7, v226
	s_waitcnt lgkmcnt(0)
	v_add_f32_e32 v226, v226, v227
	ds_bpermute_b32 v227, v8, v226
	s_waitcnt lgkmcnt(0)
	v_add_f32_e32 v226, v226, v227
	ds_bpermute_b32 v227, v9, v226
	s_waitcnt lgkmcnt(0)
	v_add_f32_e32 v226, v226, v227
	v_fmamk_f32 v226, v226, 0x3a800000, v162
	s_mov_b32 s7, 0x800000
	v_cmp_gt_f32_e32 vcc, s7, v226
	v_mul_f32_e32 v227, 0x4b800000, v226
	s_nop 0
	v_cndmask_b32_e32 v226, v226, v227, vcc
	v_rsq_f32_e32 v226, v226
	s_nop 0
	v_mul_f32_e32 v227, 0x45800000, v226
	v_cndmask_b32_e32 v228, v226, v227, vcc
	s_waitcnt vmcnt(8)
; DI unsigned pack2(float a, float b) { F2 v = {a, b}; B2 r = __builtin_convertvector(v, B2); return __builtin_bit_cast(unsigned, r); }
; DI float wave_sum(float v) { for (int o = 32; o > 0; o >>= 1) v += __shfl_xor(v, o); return v; }
; DI const float* modvec(PP p, int l, int s, int idx) { return (const float*)(p->ws + S_MOD) + ((size_t)(l * 5 + s) * 6 + idx) * DM; }
; DI void phase_rowwise(PP p, bool first, const u16* src, const float* g_post, int l_res, int gate_idx,
;                       bool write_h, const float* g_pre, int l_mod, int shift_idx, int scale_idx, bool skip_ctx) {
;     ...
; #pragma unroll
;       for (int i = 0; i < 4; ++i) {
;         int k = i * 256 + lane * 4;
;         F4 g = *(const F4*)(g_post + k); F4 gt = *(const F4*)(gate + k);
;         x[4 * i] += gt.x * (y[4 * i] * rstd * g.x); x[4 * i + 1] += gt.y * (y[4 * i + 1] * rstd * g.y);
;         x[4 * i + 2] += gt.z * (y[4 * i + 2] * rstd * g.z); x[4 * i + 3] += gt.w * (y[4 * i + 3] * rstd * g.w);
;         *(F4*)(xo + k) = mkf4(x[4 * i], x[4 * i + 1], x[4 * i + 2], x[4 * i + 3]);
;       }
;     }
;     if (write_h) {
;       float ss = 0.f;
; #pragma unroll
;       for (int i = 0; i < 16; ++i) ss += x[i] * x[i];
;       ss = wave_sum(ss);
;       float rstd = rsqrtf(ss * (1.f / DM) + EPS);
;       const float* sh = modvec(p, l_mod, s, shift_idx); const float* sc = modvec(p, l_mod, s, scale_idx);
; #pragma unroll
;       for (int i = 0; i < 4; ++i) {
;         int k = i * 256 + lane * 4;
;         F4 g = *(const F4*)(g_pre + k); F4 a = *(const F4*)(sh + k); F4 c = *(const F4*)(sc + k);
;         float h0 = x[4 * i] * rstd * g.x * (1.f + c.x) + a.x, h1 = x[4 * i + 1] * rstd * g.y * (1.f + c.y) + a.y;
;         float h2 = x[4 * i + 2] * rstd * g.z * (1.f + c.z) + a.z, h3 = x[4 * i + 3] * rstd * g.w * (1.f + c.w) + a.w;
;         *(U2*)(H + (size_t)r * DM + k) = mku2(pack2(h0, h1), pack2(h2, h3));
;       }
	v_pk_mul_f32 v[58:59], v[228:229], v[58:59] op_sel_hi:[0,1]
	v_pk_mul_f32 v[58:59], v[58:59], v[118:119]
	v_pk_fma_f32 v[10:11], v[134:135], v[58:59], v[10:11]
	v_pk_mul_f32 v[60:61], v[228:229], v[60:61] op_sel_hi:[0,1]
	v_pk_mul_f32 v[60:61], v[60:61], v[120:121]
	v_pk_fma_f32 v[12:13], v[136:137], v[60:61], v[12:13]
	v_pk_mul_f32 v[62:63], v[228:229], v[62:63] op_sel_hi:[0,1]
	v_pk_mul_f32 v[62:63], v[62:63], v[122:123]
	v_pk_fma_f32 v[14:15], v[138:139], v[62:63], v[14:15]
	v_pk_mul_f32 v[64:65], v[228:229], v[64:65] op_sel_hi:[0,1]
	v_pk_mul_f32 v[64:65], v[64:65], v[124:125]
	v_pk_fma_f32 v[16:17], v[140:141], v[64:65], v[16:17]
	v_pk_mul_f32 v[66:67], v[228:229], v[66:67] op_sel_hi:[0,1]
	v_pk_mul_f32 v[66:67], v[66:67], v[126:127]
	v_pk_fma_f32 v[18:19], v[142:143], v[66:67], v[18:19]
	v_pk_mul_f32 v[68:69], v[228:229], v[68:69] op_sel_hi:[0,1]
	v_pk_mul_f32 v[68:69], v[68:69], v[128:129]
	v_pk_fma_f32 v[20:21], v[144:145], v[68:69], v[20:21]
	v_pk_mul_f32 v[70:71], v[228:229], v[70:71] op_sel_hi:[0,1]
	v_pk_mul_f32 v[70:71], v[70:71], v[130:131]
	v_pk_fma_f32 v[22:23], v[146:147], v[70:71], v[22:23]
	v_pk_mul_f32 v[72:73], v[228:229], v[72:73] op_sel_hi:[0,1]
	v_pk_mul_f32 v[72:73], v[72:73], v[132:133]
	v_pk_fma_f32 v[24:25], v[148:149], v[72:73], v[24:25]
	global_load_dwordx4 v[118:121], v[172:173], off
	global_load_dwordx4 v[122:125], v[172:173], off offset:1024
	global_load_dwordx4 v[126:129], v[172:173], off offset:2048
	global_load_dwordx4 v[130:133], v[172:173], off offset:3072
	global_load_dwordx4 v[134:137], v[222:223], off
	global_load_dwordx4 v[138:141], v[222:223], off offset:1024
	global_load_dwordx4 v[142:145], v[222:223], off offset:2048
	global_load_dwordx4 v[146:149], v[222:223], off offset:3072
	global_load_dwordx4 v[150:153], v[224:225], off
	global_load_dwordx4 v[154:157], v[224:225], off offset:1024
	global_load_dwordx4 v[158:161], v[224:225], off offset:2048
	global_load_dwordx4 v[166:169], v[224:225], off offset:3072
	global_store_dwordx4 v[188:189], v[10:13], off nt
	global_store_dwordx4 v[188:189], v[14:17], off offset:1024 nt
	global_store_dwordx4 v[188:189], v[18:21], off offset:2048 nt
	global_store_dwordx4 v[188:189], v[22:25], off offset:3072 nt
	v_mul_f32_e32 v226, v10, v10
	v_mul_f32_e32 v227, v11, v11
	v_add_f32_e32 v226, v226, v227
	v_mul_f32_e32 v227, v12, v12
	v_add_f32_e32 v226, v227, v226
	v_mul_f32_e32 v227, v13, v13
	v_add_f32_e32 v226, v227, v226
	v_mul_f32_e32 v227, v14, v14
	v_add_f32_e32 v226, v227, v226
	v_mul_f32_e32 v227, v15, v15
	v_add_f32_e32 v226, v227, v226
	v_mul_f32_e32 v227, v16, v16
	v_add_f32_e32 v226, v227, v226
	v_mul_f32_e32 v227, v17, v17
	v_add_f32_e32 v226, v227, v226
	v_mul_f32_e32 v227, v18, v18
	v_add_f32_e32 v226, v227, v226
	v_mul_f32_e32 v227, v19, v19
	v_add_f32_e32 v226, v227, v226
	v_mul_f32_e32 v227, v20, v20
	v_add_f32_e32 v226, v227, v226
	v_mul_f32_e32 v227, v21, v21
	v_add_f32_e32 v226, v227, v226
	v_mul_f32_e32 v227, v22, v22
	v_add_f32_e32 v226, v227, v226
	v_mul_f32_e32 v227, v23, v23
	v_add_f32_e32 v226, v227, v226
	v_mul_f32_e32 v227, v24, v24
	v_add_f32_e32 v226, v227, v226
	v_mul_f32_e32 v227, v25, v25
	v_add_f32_e32 v226, v227, v226
	ds_bpermute_b32 v227, v4, v226
	s_waitcnt lgkmcnt(0)
	v_add_f32_e32 v226, v226, v227
	ds_bpermute_b32 v227, v5, v226
	s_waitcnt lgkmcnt(0)
	v_add_f32_e32 v226, v226, v227
	ds_bpermute_b32 v227, v6, v226
	s_waitcnt lgkmcnt(0)
	v_add_f32_e32 v226, v226, v227
	ds_bpermute_b32 v227, v7, v226
	s_waitcnt lgkmcnt(0)
	v_add_f32_e32 v226, v226, v227
	ds_bpermute_b32 v227, v8, v226
	s_waitcnt lgkmcnt(0)
	v_add_f32_e32 v226, v226, v227
	ds_bpermute_b32 v227, v9, v226
	s_waitcnt lgkmcnt(0)
	v_add_f32_e32 v226, v226, v227
	v_fmamk_f32 v226, v226, 0x3a800000, v162
	s_mov_b32 s7, 0x800000
	v_cmp_gt_f32_e32 vcc, s7, v226
	v_mul_f32_e32 v227, 0x4b800000, v226
	s_nop 0
	v_cndmask_b32_e32 v226, v226, v227, vcc
	v_rsq_f32_e32 v226, v226
	s_nop 0
	v_mul_f32_e32 v227, 0x45800000, v226
	v_cndmask_b32_e32 v228, v226, v227, vcc
	s_waitcnt vmcnt(4)
	v_pk_mul_f32 v[10:11], v[10:11], v[228:229] op_sel_hi:[1,0]
	v_pk_mul_f32 v[10:11], v[118:119], v[10:11]
	v_pk_add_f32 v[58:59], v[150:151], 1.0 op_sel_hi:[1,0]
	s_nop 0
	v_pk_fma_f32 v[10:11], v[58:59], v[10:11], v[134:135]
	v_pk_mul_f32 v[12:13], v[12:13], v[228:229] op_sel_hi:[1,0]
	v_pk_mul_f32 v[12:13], v[120:121], v[12:13]
	v_pk_add_f32 v[60:61], v[152:153], 1.0 op_sel_hi:[1,0]
	s_nop 0
	v_pk_fma_f32 v[12:13], v[60:61], v[12:13], v[136:137]
	v_cvt_pk_bf16_f32 v66, v10, v11
	v_cvt_pk_bf16_f32 v67, v12, v13
	global_store_dwordx2 v[218:219], v[66:67], off
	s_nop 1
	v_pk_mul_f32 v[14:15], v[14:15], v[228:229] op_sel_hi:[1,0]
	v_pk_mul_f32 v[14:15], v[122:123], v[14:15]
	v_pk_add_f32 v[58:59], v[154:155], 1.0 op_sel_hi:[1,0]
	s_nop 0
	v_pk_fma_f32 v[14:15], v[58:59], v[14:15], v[138:139]
	v_pk_mul_f32 v[16:17], v[16:17], v[228:229] op_sel_hi:[1,0]
	v_pk_mul_f32 v[16:17], v[124:125], v[16:17]
	v_pk_add_f32 v[60:61], v[156:157], 1.0 op_sel_hi:[1,0]
	s_nop 0
	v_pk_fma_f32 v[16:17], v[60:61], v[16:17], v[140:141]
	v_cvt_pk_bf16_f32 v66, v14, v15
	v_cvt_pk_bf16_f32 v67, v16, v17
	global_store_dwordx2 v[218:219], v[66:67], off offset:512
	s_nop 1
	v_pk_mul_f32 v[18:19], v[18:19], v[228:229] op_sel_hi:[1,0]
	v_pk_mul_f32 v[18:19], v[126:127], v[18:19]
	v_pk_add_f32 v[58:59], v[158:159], 1.0 op_sel_hi:[1,0]
	s_nop 0
	v_pk_fma_f32 v[18:19], v[58:59], v[18:19], v[142:143]
	v_pk_mul_f32 v[20:21], v[20:21], v[228:229] op_sel_hi:[1,0]
	v_pk_mul_f32 v[20:21], v[128:129], v[20:21]
	v_pk_add_f32 v[60:61], v[160:161], 1.0 op_sel_hi:[1,0]
	s_nop 0
	v_pk_fma_f32 v[20:21], v[60:61], v[20:21], v[144:145]
	v_cvt_pk_bf16_f32 v66, v18, v19
	v_cvt_pk_bf16_f32 v67, v20, v21
	global_store_dwordx2 v[218:219], v[66:67], off offset:1024
	s_nop 1
	v_pk_mul_f32 v[22:23], v[22:23], v[228:229] op_sel_hi:[1,0]
	v_pk_mul_f32 v[22:23], v[130:131], v[22:23]
	v_pk_add_f32 v[58:59], v[166:167], 1.0 op_sel_hi:[1,0]
	s_nop 0
	v_pk_fma_f32 v[22:23], v[58:59], v[22:23], v[146:147]
	v_pk_mul_f32 v[24:25], v[24:25], v[228:229] op_sel_hi:[1,0]
	v_pk_mul_f32 v[24:25], v[132:133], v[24:25]
	v_pk_add_f32 v[60:61], v[168:169], 1.0 op_sel_hi:[1,0]
	s_nop 0
	v_pk_fma_f32 v[24:25], v[60:61], v[24:25], v[148:149]
	v_cvt_pk_bf16_f32 v66, v22, v23
	v_cvt_pk_bf16_f32 v67, v24, v25
	global_store_dwordx2 v[218:219], v[66:67], off offset:1536
	s_nop 1
	s_branch .Lrw17_noh

; DI int get_tid() { int t = threadIdx.x; asm volatile("" : "+v"(t)); return t; }
; DI int get_bid() { int t = blockIdx.x; asm volatile("" : "+s"(t)); return t; }
; DI void phase_rowwise(PP p, bool first, const u16* src, const float* g_post, int l_res, int gate_idx,
;                       bool write_h, const float* g_pre, int l_mod, int shift_idx, int scale_idx, bool skip_ctx) {
;   const int lane = get_tid() & 63, w = get_tid() >> 6;
;   u16* H = (u16*)(p->ws + H_OFF);
;   for (int r = get_bid() * 4 + w; r < ROWS; r += gridDim.x * 4) {
;     int b = r / TT, t = r - b * TT;
;     if (skip_ctx && t < CTX) continue;
;     int s = t < CTX ? 4 : b;
;     const float* xin = xrow_in(p, r, first);
;     float x[16];
; #pragma unroll
;     for (int i = 0; i < 4; ++i) { F4 v = *(const F4*)(xin + i * 256 + lane * 4); x[4 * i] = v.x; x[4 * i + 1] = v.y; x[4 * i + 2] = v.z; x[4 * i + 3] = v.w; }
.LBB0_1190:
	s_andn2_b64 vcc, exec, s[0:1]
	s_cbranch_vccnz .LBB0_1195
	v_lshrrev_b32_e32 v0, 6, v163
	v_readlane_b32 s2, v249, 0
	v_readfirstlane_b32 s3, v0
	v_and_b32_e32 v0, 63, v163
	s_lshl_b32 s0, s2, 2
	s_add_i32 s0, s0, s3
	v_lshlrev_b32_e32 v2, 4, v0
	v_lshlrev_b32_e32 v3, 3, v0
	v_xor_b32_e32 v4, 32, v0
	v_xor_b32_e32 v5, 16, v0
	v_xor_b32_e32 v6, 8, v0
	v_xor_b32_e32 v7, 4, v0
	v_xor_b32_e32 v8, 2, v0
	v_xor_b32_e32 v9, 1, v0
	v_lshlrev_b32_e32 v4, 2, v4
	v_lshlrev_b32_e32 v5, 2, v5
	v_lshlrev_b32_e32 v6, 2, v6
	v_lshlrev_b32_e32 v7, 2, v7
	v_lshlrev_b32_e32 v8, 2, v8
	v_lshlrev_b32_e32 v9, 2, v9
	v_mov_b32_e32 v43, 0
	v_mov_b32_e32 v229, 0
	v_readlane_b32 s12, v251, 35
	v_readlane_b32 s13, v251, 36
	s_nop 0
	s_load_dwordx2 s[4:5], s[12:13], 0x30
	s_load_dwordx2 s[6:7], s[12:13], 0x0
	s_load_dwordx2 s[8:9], s[12:13], 0x10
	s_waitcnt lgkmcnt(0)
	v_mov_b32_e32 v42, v2
	v_lshl_add_u64 v[172:173], s[4:5], 0, v[42:43]
	v_mov_b32_e32 v234, s6
	v_mov_b32_e32 v235, s7
	v_mov_b32_e32 v236, s8
	v_mov_b32_e32 v237, s9
	s_add_u32 s6, s48, 0x2b00000
	s_addc_u32 s7, s49, 0
	v_lshl_add_u64 v[176:177], s[6:7], 0, v[42:43]
	s_add_u32 s6, s6, 0x1000
	s_addc_u32 s7, s7, 0
	v_lshl_add_u64 v[178:179], s[6:7], 0, v[42:43]
	v_mov_b32_e32 v42, v3
	s_add_u32 s6, s48, 0x3900000
	s_addc_u32 s7, s49, 0
	v_lshl_add_u64 v[182:183], s[6:7], 0, v[42:43]
	s_cmp_ge_u32 s0, 0x8400
	s_cbranch_scc1 .Lrw2_done
	s_cmp_ge_u32 s0, 0x2100
	s_cselect_b32 s2, 1, 0
	s_cmp_ge_u32 s0, 0x4200
	s_addc_u32 s2, s2, 0
	s_cmp_ge_u32 s0, 0x6300
	s_addc_u32 s2, s2, 0
	s_mul_i32 s3, s2, 0x2100
	s_sub_i32 s3, s0, s3
	s_lshl_b32 s7, s2, 8
	s_add_i32 s7, s7, s3
	s_lshl_b32 s9, s2, 13
	s_add_i32 s9, s9, s3
	s_add_i32 s9, s9, 0xffffff00
	s_cmp_lt_u32 s3, 0x100
	s_cselect_b32 s7, s7, s9
	s_cselect_b32 s5, 4, s2
	s_cselect_b64 s[12:13], -1, 0
	s_lshl_b32 s7, s7, 12
	v_add_u32_e32 v42, s7, v2
	v_cndmask_b32_e64 v190, v234, v236, s[12:13]
	v_cndmask_b32_e64 v191, v235, v237, s[12:13]
	v_lshl_add_u64 v[190:191], v[190:191], 0, v[42:43]
	global_load_dwordx4 v[26:29], v[190:191], off nt
	global_load_dwordx4 v[30:33], v[190:191], off offset:1024 nt
	global_load_dwordx4 v[34:37], v[190:191], off offset:2048 nt
	global_load_dwordx4 v[38:41], v[190:191], off offset:3072 nt
	s_waitcnt vmcnt(0)
; DI void phase_rowwise(PP p, bool first, const u16* src, const float* g_post, int l_res, int gate_idx,
;                       bool write_h, const float* g_pre, int l_mod, int shift_idx, int scale_idx, bool skip_ctx) {
;     ...
;   for (int r = get_bid() * 4 + w; r < ROWS; r += gridDim.x * 4) {
;     int b = r / TT, t = r - b * TT;
;     if (skip_ctx && t < CTX) continue;
;     int s = t < CTX ? 4 : b;
;     const float* xin = xrow_in(p, r, first);
;     float x[16];
; #pragma unroll
;     for (int i = 0; i < 4; ++i) { F4 v = *(const F4*)(xin + i * 256 + lane * 4); x[4 * i] = v.x; x[4 * i + 1] = v.y; x[4 * i + 2] = v.z; x[4 * i + 3] = v.w; }
;     if (src) {
;       float y[16]; float ss = 0.f;
; #pragma unroll
;       for (int i = 0; i < 4; ++i) { U2 v = *(const U2*)(src + (size_t)r * DM + i * 256 + lane * 4);
;         y[4 * i] = lo2f(v.x); y[4 * i + 1] = hi2f(v.x); y[4 * i + 2] = lo2f(v.y); y[4 * i + 3] = hi2f(v.y); }
; #pragma unroll
;       for (int i = 0; i < 16; ++i) ss += y[i] * y[i];
;       ss = wave_sum(ss);
;       float rstd = rsqrtf(ss * (1.f / DM) + EPS);
;       const float* gate = modvec(p, l_res, s, gate_idx);
;       float* xo = xrow_out(p, r);
; #pragma unroll
;       for (int i = 0; i < 4; ++i) {
;         int k = i * 256 + lane * 4;
;         F4 g = *(const F4*)(g_post + k); F4 gt = *(const F4*)(gate + k);
;         x[4 * i] += gt.x * (y[4 * i] * rstd * g.x); x[4 * i + 1] += gt.y * (y[4 * i + 1] * rstd * g.y);
;         x[4 * i + 2] += gt.z * (y[4 * i + 2] * rstd * g.z); x[4 * i + 3] += gt.w * (y[4 * i + 3] * rstd * g.w);
;         *(F4*)(xo + k) = mkf4(x[4 * i], x[4 * i + 1], x[4 * i + 2], x[4 * i + 3]);
;       }
;     }
;     if (write_h) {
;       float ss = 0.f;
; #pragma unroll
;       for (int i = 0; i < 16; ++i) ss += x[i] * x[i];
;       ss = wave_sum(ss);
;       float rstd = rsqrtf(ss * (1.f / DM) + EPS);
;       const float* sh = modvec(p, l_mod, s, shift_idx); const float* sc = modvec(p, l_mod, s, scale_idx);
; #pragma unroll
;       for (int i = 0; i < 4; ++i) {
;         int k = i * 256 + lane * 4;
;         F4 g = *(const F4*)(g_pre + k); F4 a = *(const F4*)(sh + k); F4 c = *(const F4*)(sc + k);
;         float h0 = x[4 * i] * rstd * g.x * (1.f + c.x) + a.x, h1 = x[4 * i + 1] * rstd * g.y * (1.f + c.y) + a.y;
;         float h2 = x[4 * i + 2] * rstd * g.z * (1.f + c.z) + a.z, h3 = x[4 * i + 3] * rstd * g.w * (1.f + c.w) + a.w;
.Lrw2_loop:
	v_mov_b32_e32 v10, v26
	v_mov_b32_e32 v11, v27
	v_mov_b32_e32 v12, v28
	v_mov_b32_e32 v13, v29
	v_mov_b32_e32 v14, v30
	v_mov_b32_e32 v15, v31
	v_mov_b32_e32 v16, v32
	v_mov_b32_e32 v17, v33
	v_mov_b32_e32 v18, v34
	v_mov_b32_e32 v19, v35
	v_mov_b32_e32 v20, v36
	v_mov_b32_e32 v21, v37
	v_mov_b32_e32 v22, v38
	v_mov_b32_e32 v23, v39
	v_mov_b32_e32 v24, v40
	v_mov_b32_e32 v25, v41
	s_mov_b32 s4, s5
	s_mul_i32 s7, s4, 0x6000
	v_mov_b32_e32 v42, s7
	v_lshl_add_u64 v[222:223], v[176:177], 0, v[42:43]
	v_lshl_add_u64 v[224:225], v[178:179], 0, v[42:43]
	s_lshl_b32 s7, s0, 11
	v_mov_b32_e32 v42, s7
	v_lshl_add_u64 v[218:219], v[182:183], 0, v[42:43]
	global_load_dwordx4 v[118:121], v[172:173], off
	global_load_dwordx4 v[122:125], v[172:173], off offset:1024
	global_load_dwordx4 v[126:129], v[172:173], off offset:2048
	global_load_dwordx4 v[130:133], v[172:173], off offset:3072
	global_load_dwordx4 v[134:137], v[222:223], off
	global_load_dwordx4 v[138:141], v[222:223], off offset:1024
	global_load_dwordx4 v[142:145], v[222:223], off offset:2048
	global_load_dwordx4 v[146:149], v[222:223], off offset:3072
	global_load_dwordx4 v[150:153], v[224:225], off
	global_load_dwordx4 v[154:157], v[224:225], off offset:1024
	global_load_dwordx4 v[158:161], v[224:225], off offset:2048
	global_load_dwordx4 v[166:169], v[224:225], off offset:3072
	s_add_i32 s1, s0, s90
	s_mov_b32 s8, 0
	s_cmp_ge_u32 s1, 0x8400
	s_cselect_b32 s8, 1, 0
	s_cselect_b32 s1, s0, s1
	s_cmp_ge_u32 s1, 0x2100
	s_cselect_b32 s2, 1, 0
	s_cmp_ge_u32 s1, 0x4200
	s_addc_u32 s2, s2, 0
	s_cmp_ge_u32 s1, 0x6300
	s_addc_u32 s2, s2, 0
	s_mul_i32 s3, s2, 0x2100
	s_sub_i32 s3, s1, s3
	s_lshl_b32 s7, s2, 8
	s_add_i32 s7, s7, s3
	s_lshl_b32 s9, s2, 13
	s_add_i32 s9, s9, s3
	s_add_i32 s9, s9, 0xffffff00
	s_cmp_lt_u32 s3, 0x100
	s_cselect_b32 s7, s7, s9
	s_cselect_b32 s5, 4, s2
	s_cselect_b64 s[12:13], -1, 0
	s_lshl_b32 s7, s7, 12
	v_add_u32_e32 v42, s7, v2
	v_cndmask_b32_e64 v190, v234, v236, s[12:13]
	v_cndmask_b32_e64 v191, v235, v237, s[12:13]
	v_lshl_add_u64 v[190:191], v[190:191], 0, v[42:43]
	global_load_dwordx4 v[26:29], v[190:191], off nt
	global_load_dwordx4 v[30:33], v[190:191], off offset:1024 nt
	global_load_dwordx4 v[34:37], v[190:191], off offset:2048 nt
	global_load_dwordx4 v[38:41], v[190:191], off offset:3072 nt
	v_mul_f32_e32 v226, v11, v11
	v_fmac_f32_e32 v226, v10, v10
	v_fmac_f32_e32 v226, v12, v12
	v_fmac_f32_e32 v226, v13, v13
	v_fmac_f32_e32 v226, v14, v14
	v_fmac_f32_e32 v226, v15, v15
	v_fmac_f32_e32 v226, v16, v16
	v_fmac_f32_e32 v226, v17, v17
	v_fmac_f32_e32 v226, v18, v18
	v_fmac_f32_e32 v226, v19, v19
	v_fmac_f32_e32 v226, v20, v20
	v_fmac_f32_e32 v226, v21, v21
	v_mul_f32_e32 v227, v22, v22
	v_add_f32_e32 v226, v227, v226
	v_mul_f32_e32 v227, v23, v23
	v_add_f32_e32 v226, v227, v226
	v_mul_f32_e32 v227, v24, v24
	v_add_f32_e32 v226, v227, v226
	v_mul_f32_e32 v227, v25, v25
	v_add_f32_e32 v226, v227, v226
	ds_bpermute_b32 v227, v4, v226
	s_waitcnt lgkmcnt(0)
	v_add_f32_e32 v226, v226, v227
	ds_bpermute_b32 v227, v5, v226
	s_waitcnt lgkmcnt(0)
	v_add_f32_e32 v226, v226, v227
	ds_bpermute_b32 v227, v6, v226
	s_waitcnt lgkmcnt(0)
	v_add_f32_e32 v226, v226, v227
	ds_bpermute_b32 v227, v7, v226
	s_waitcnt lgkmcnt(0)
	v_add_f32_e32 v226, v226, v227
	ds_bpermute_b32 v227, v8, v226
	s_waitcnt lgkmcnt(0)
	v_add_f32_e32 v226, v226, v227
	ds_bpermute_b32 v227, v9, v226
	s_waitcnt lgkmcnt(0)
	v_add_f32_e32 v226, v226, v227
	v_fmamk_f32 v226, v226, 0x3a800000, v162
	s_mov_b32 s7, 0x800000
	v_cmp_gt_f32_e32 vcc, s7, v226
	v_mul_f32_e32 v227, 0x4b800000, v226
	s_nop 0
	v_cndmask_b32_e32 v226, v226, v227, vcc
	v_rsq_f32_e32 v226, v226
	s_nop 0
	v_mul_f32_e32 v227, 0x45800000, v226
	v_cndmask_b32_e32 v228, v226, v227, vcc
	s_waitcnt vmcnt(4)
	v_pk_mul_f32 v[10:11], v[10:11], v[228:229] op_sel_hi:[1,0]
	v_pk_mul_f32 v[10:11], v[118:119], v[10:11]
	v_pk_add_f32 v[44:45], v[150:151], 1.0 op_sel_hi:[1,0]
	s_nop 0
	v_pk_fma_f32 v[10:11], v[44:45], v[10:11], v[134:135]
	v_pk_mul_f32 v[12:13], v[12:13], v[228:229] op_sel_hi:[1,0]
	v_pk_mul_f32 v[12:13], v[120:121], v[12:13]
	v_pk_add_f32 v[46:47], v[152:153], 1.0 op_sel_hi:[1,0]
	s_nop 0
	v_pk_fma_f32 v[12:13], v[46:47], v[12:13], v[136:137]
	v_cvt_pk_bf16_f32 v48, v10, v11
	v_cvt_pk_bf16_f32 v49, v12, v13
	global_store_dwordx2 v[218:219], v[48:49], off
	s_nop 1
	v_pk_mul_f32 v[14:15], v[14:15], v[228:229] op_sel_hi:[1,0]
	v_pk_mul_f32 v[14:15], v[122:123], v[14:15]
	v_pk_add_f32 v[44:45], v[154:155], 1.0 op_sel_hi:[1,0]
	s_nop 0
	v_pk_fma_f32 v[14:15], v[44:45], v[14:15], v[138:139]
	v_pk_mul_f32 v[16:17], v[16:17], v[228:229] op_sel_hi:[1,0]
	v_pk_mul_f32 v[16:17], v[124:125], v[16:17]
	v_pk_add_f32 v[46:47], v[156:157], 1.0 op_sel_hi:[1,0]
	s_nop 0
	v_pk_fma_f32 v[16:17], v[46:47], v[16:17], v[140:141]
	v_cvt_pk_bf16_f32 v48, v14, v15
	v_cvt_pk_bf16_f32 v49, v16, v17
	global_store_dwordx2 v[218:219], v[48:49], off offset:512
	s_nop 1
	v_pk_mul_f32 v[18:19], v[18:19], v[228:229] op_sel_hi:[1,0]
	v_pk_mul_f32 v[18:19], v[126:127], v[18:19]
	v_pk_add_f32 v[44:45], v[158:159], 1.0 op_sel_hi:[1,0]
	s_nop 0
	v_pk_fma_f32 v[18:19], v[44:45], v[18:19], v[142:143]
	v_pk_mul_f32 v[20:21], v[20:21], v[228:229] op_sel_hi:[1,0]
	v_pk_mul_f32 v[20:21], v[128:129], v[20:21]
	v_pk_add_f32 v[46:47], v[160:161], 1.0 op_sel_hi:[1,0]
	s_nop 0
	v_pk_fma_f32 v[20:21], v[46:47], v[20:21], v[144:145]
	v_cvt_pk_bf16_f32 v48, v18, v19
	v_cvt_pk_bf16_f32 v49, v20, v21
	global_store_dwordx2 v[218:219], v[48:49], off offset:1024
	s_nop 1
	v_pk_mul_f32 v[22:23], v[22:23], v[228:229] op_sel_hi:[1,0]
	v_pk_mul_f32 v[22:23], v[130:131], v[22:23]
	v_pk_add_f32 v[44:45], v[166:167], 1.0 op_sel_hi:[1,0]
	s_nop 0
	v_pk_fma_f32 v[22:23], v[44:45], v[22:23], v[146:147]
	v_pk_mul_f32 v[24:25], v[24:25], v[228:229] op_sel_hi:[1,0]
	v_pk_mul_f32 v[24:25], v[132:133], v[24:25]
	v_pk_add_f32 v[46:47], v[168:169], 1.0 op_sel_hi:[1,0]
	s_nop 0
	v_pk_fma_f32 v[24:25], v[46:47], v[24:25], v[148:149]
	v_cvt_pk_bf16_f32 v48, v22, v23
	v_cvt_pk_bf16_f32 v49, v24, v25
	global_store_dwordx2 v[218:219], v[48:49], off offset:1536
	s_nop 1
	s_waitcnt vmcnt(4)
	s_cmp_eq_u32 s8, 1
	s_cbranch_scc1 .Lrw2_done
	s_mov_b32 s0, s1
	s_branch .Lrw2_loop
